# attention PV MFMAs issued k-major: the same P fragment (A operand) feeds 4 consecutive MFMAs into the 4 O blocks, instead of 4 consecutive k-steps on one accumulator
# speedup vs baseline: 1.0029x; 1.0029x over previous
; __device__ __forceinline__ void partialSM(f32x16& p0, f32x16& p1, float& m_ref, float& alpha, bool first) {
;   constexpr float THRL = THR * 1.4426950408889634f;
;   float pmax = p0[0];
; #pragma unroll
;   for (int r = 1; r < 16; ++r) pmax = fmaxf(pmax, p0[r]);
; #pragma unroll
;   for (int r = 0; r < 16; ++r) pmax = fmaxf(pmax, p1[r]);
;   { auto rr = __builtin_amdgcn_permlane32_swap(__float_as_uint(pmax), __float_as_uint(pmax), false, false);
;     pmax = fmaxf(__uint_as_float(rr[0]), __uint_as_float(rr[1])); }
;   if (__builtin_expect(!first && __all(pmax <= THRL), 1)) { alpha = 1.f; }
;   else { const float dl = first ? pmax : fmaxf(pmax, 0.f); m_ref += dl; alpha = first ? 1.f : __builtin_amdgcn_exp2f(-dl);
; #pragma unroll
;     for (int r = 0; r < 16; ++r) { p0[r] -= dl; p1[r] -= dl; } }
; #pragma unroll
;   for (int r = 0; r < 16; ++r) p0[r] = __builtin_amdgcn_exp2f(p0[r]);
; }
; __device__ __forceinline__ void finishSM(f32x16& p0, f32x16& p1, float alpha, float& l_reg, bf16x8& pa0, bf16x8& pa1, bf16x8& pa2, bf16x8& pa3) {
; #pragma unroll
;   for (int r = 0; r < 16; ++r) p1[r] = __builtin_amdgcn_exp2f(p1[r]);
;   float ps = 0;
; #pragma unroll
;   for (int r = 0; r < 16; ++r) ps += p0[r];
; #pragma unroll
;   for (int r = 0; r < 16; ++r) ps += p1[r];
;   { auto rr = __builtin_amdgcn_permlane32_swap(__float_as_uint(ps), __float_as_uint(ps), false, false);
;     ps = __uint_as_float(rr[0]) + __uint_as_float(rr[1]); }
;   l_reg = l_reg * alpha + ps;
;     ...
;   PK4(p0, 0, pa0); PK4(p0, 8, pa1); PK4(p1, 0, pa2); PK4(p1, 8, pa3);
;     ...
; }
; __device__ __forceinline__ void qkt(f32x16& p0, f32x16& p1, const char* Ks, const bf16x8* qr, int r32, int hi, float m_ref) {
; #pragma unroll
;   for (int r = 0; r < 16; ++r) { p0[r] = -m_ref; p1[r] = -m_ref; }
; __device__ __forceinline__ void attn_unit(const bf16_t* __restrict__ Qb, const bf16_t* __restrict__ Kh, const bf16_t* __restrict__ Vh, int seq, char* lds,
;                                           int mode, float* scratch, float lam, float gscale, const float* __restrict__ subg, bf16_t* outp) {
;     ...
;   for (int j = 1; j + 1 < NT; j += 2) {
;     SBAR(); qkt(pB0, pB1, K_lds + bc * SHM_K, qr, r32, hi, m_reg);
;     finishSM(pA0, pA1, alA, l_reg, pa0, pa1, pa2, pa3); SBAR();
;     SLOAD(SO, (j + 2) * KVBLK); SBAR();
;     pv_d0(o, vb0 + bp * SHM_V, pa0, pa1, pa2, pa3); partialSM(pB0, pB1, m_reg, alB, false);
.Lat_loop:
	s_barrier
	s_waitcnt lgkmcnt(7)
	v_mfma_f32_32x32x16_bf16 v[96:111], v[182:185], v[124:127], v[128:143]
	ds_read_b64_tr_b16 v[182:183], v172 offset:0x0
	ds_read_b64_tr_b16 v[184:185], v172 offset:0x800
	v_add_f32_e32 v159, v64, v65
	v_cvt_pk_bf16_f32 v64, v64, v65
	v_add_f32_e32 v160, v66, v67
	v_cvt_pk_bf16_f32 v65, v66, v67
	v_add_f32_e32 v159, v68, v159
	v_add_f32_e32 v160, v69, v160
	v_cvt_pk_bf16_f32 v66, v68, v69
	s_waitcnt lgkmcnt(8)
	v_mfma_f32_32x32x16_bf16 v[236:251], v[186:189], v[124:127], v[128:143]
	ds_read_b64_tr_b16 v[186:187], v172 offset:0x200
	ds_read_b64_tr_b16 v[188:189], v172 offset:0xa00
	v_add_f32_e32 v159, v70, v159
	v_add_f32_e32 v160, v71, v160
	v_cvt_pk_bf16_f32 v67, v70, v71
	v_add_f32_e32 v159, v72, v159
	v_add_f32_e32 v160, v73, v160
	v_cvt_pk_bf16_f32 v68, v72, v73
	v_add_f32_e32 v159, v74, v159
	s_waitcnt lgkmcnt(9)
	v_mfma_f32_32x32x16_bf16 v[96:111], v[190:193], v[120:123], v[96:111]
	ds_read_b64_tr_b16 v[190:191], v172 offset:0x400
	ds_read_b64_tr_b16 v[192:193], v172 offset:0xc00
	v_add_f32_e32 v160, v75, v160
	v_cvt_pk_bf16_f32 v69, v74, v75
	v_add_f32_e32 v159, v76, v159
	v_add_f32_e32 v160, v77, v160
	v_cvt_pk_bf16_f32 v70, v76, v77
	v_add_f32_e32 v159, v78, v159
	v_add_f32_e32 v160, v79, v160
	s_waitcnt lgkmcnt(10)
	v_mfma_f32_32x32x16_bf16 v[236:251], v[194:197], v[120:123], v[236:251]
	ds_read_b64_tr_b16 v[194:195], v172 offset:0x600
	ds_read_b64_tr_b16 v[196:197], v172 offset:0xe00
	s_mov_b32 m0, s20
	s_nop 0
	global_load_lds_dwordx4 v233, s[24:25]
	s_add_i32 m0, m0, 0x400
	s_nop 0
	global_load_lds_dwordx4 v234, s[24:25]
	s_mov_b32 m0, s58
	s_nop 0
	global_load_lds_dwordx4 v232, s[24:25]
	s_add_u32 s24, s24, 0x10000
	s_addc_u32 s25, s25, 0
	v_cvt_pk_bf16_f32 v71, v78, v79
	v_add_f32_e32 v159, v80, v159
	v_add_f32_e32 v160, v81, v160
	v_cvt_pk_bf16_f32 v72, v80, v81
	v_add_f32_e32 v159, v82, v159
	v_add_f32_e32 v160, v83, v160
	v_cvt_pk_bf16_f32 v73, v82, v83
	s_waitcnt lgkmcnt(11)
	v_mfma_f32_32x32x16_bf16 v[96:111], v[198:201], v[116:119], v[96:111]
	ds_read_b64_tr_b16 v[198:199], v172 offset:0x1000
	ds_read_b64_tr_b16 v[200:201], v172 offset:0x1800
	v_add_f32_e32 v159, v84, v159
	v_add_f32_e32 v160, v85, v160
	v_cvt_pk_bf16_f32 v74, v84, v85
	v_add_f32_e32 v159, v86, v159
	v_add_f32_e32 v160, v87, v160
	v_cvt_pk_bf16_f32 v75, v86, v87
	v_add_f32_e32 v159, v88, v159
	s_waitcnt lgkmcnt(12)
	v_mfma_f32_32x32x16_bf16 v[236:251], v[202:205], v[116:119], v[236:251]
	ds_read_b64_tr_b16 v[202:203], v172 offset:0x1200
	ds_read_b64_tr_b16 v[204:205], v172 offset:0x1a00
	v_add_f32_e32 v160, v89, v160
	v_cvt_pk_bf16_f32 v76, v88, v89
	v_add_f32_e32 v159, v90, v159
	v_add_f32_e32 v160, v91, v160
	v_cvt_pk_bf16_f32 v77, v90, v91
	v_add_f32_e32 v159, v92, v159
	v_add_f32_e32 v160, v93, v160
	s_waitcnt lgkmcnt(13)
	v_mfma_f32_32x32x16_bf16 v[96:111], v[206:209], v[112:115], v[96:111]
	ds_read_b64_tr_b16 v[206:207], v172 offset:0x1400
	ds_read_b64_tr_b16 v[208:209], v172 offset:0x1c00
	v_cvt_pk_bf16_f32 v78, v92, v93
	v_add_f32_e32 v159, v94, v159
	v_add_f32_e32 v160, v95, v160
	v_cvt_pk_bf16_f32 v79, v94, v95
	v_add_f32_e32 v159, v159, v160
	v_fma_f32 v167, v167, v235, v159
	s_waitcnt lgkmcnt(14)
	v_mfma_f32_32x32x16_bf16 v[236:251], v[210:213], v[112:115], v[236:251]
	s_waitcnt lgkmcnt(12)
	v_mfma_f32_32x32x16_bf16 v[0:15], v[64:67], v[182:185], v[0:15]
	ds_read_b64_tr_b16 v[210:211], v172 offset:0x1600
	ds_read_b64_tr_b16 v[212:213], v172 offset:0x1e00
	v_max3_f32 v161, v96, v97, v98
	v_max3_f32 v161, v161, v99, v100
	v_max3_f32 v161, v161, v101, v102
	v_max3_f32 v161, v161, v103, v104
	s_waitcnt lgkmcnt(12)
	v_mfma_f32_32x32x16_bf16 v[48:63], v[64:67], v[186:189], v[48:63]
	ds_read_b64_tr_b16 v[182:183], v172 offset:0x2000
	ds_read_b64_tr_b16 v[184:185], v172 offset:0x2800
	v_max3_f32 v161, v161, v105, v106
	v_max3_f32 v161, v161, v107, v108
	v_max3_f32 v161, v161, v109, v110
	v_max_f32_e32 v161, v161, v111
	s_waitcnt lgkmcnt(12)
	v_mfma_f32_32x32x16_bf16 v[32:47], v[64:67], v[190:193], v[32:47]
	ds_read_b64_tr_b16 v[186:187], v172 offset:0x2200
	ds_read_b64_tr_b16 v[188:189], v172 offset:0x2a00
	v_max3_f32 v216, v236, v237, v238
	v_max3_f32 v216, v216, v239, v240
	v_max3_f32 v216, v216, v241, v242
	v_max3_f32 v216, v216, v243, v244
	s_waitcnt lgkmcnt(12)
	v_mfma_f32_32x32x16_bf16 v[16:31], v[64:67], v[194:197], v[16:31]
	ds_read_b64_tr_b16 v[190:191], v172 offset:0x2400
	ds_read_b64_tr_b16 v[192:193], v172 offset:0x2c00
	v_max3_f32 v216, v216, v245, v246
	v_max3_f32 v216, v216, v247, v248
	v_max3_f32 v216, v216, v249, v250
	v_max_f32_e32 v216, v216, v251
	v_max_f32_e32 v161, v161, v216
	v_cmp_ge_f32_e32 vcc, s66, v161
	s_cmp_eq_u64 vcc, exec
	s_cbranch_scc0 .Lat_rare0
	v_mov_b32_e32 v158, 1.0
; #define SBAR() __builtin_amdgcn_sched_barrier(0)
; __device__ __forceinline__ void partialSM(f32x16& p0, f32x16& p1, float& m_ref, float& alpha, bool first) {
;   constexpr float THRL = THR * 1.4426950408889634f;
;   float pmax = p0[0];
; #pragma unroll
;   for (int r = 1; r < 16; ++r) pmax = fmaxf(pmax, p0[r]);
; #pragma unroll
;   for (int r = 0; r < 16; ++r) pmax = fmaxf(pmax, p1[r]);
;   { auto rr = __builtin_amdgcn_permlane32_swap(__float_as_uint(pmax), __float_as_uint(pmax), false, false);
;     pmax = fmaxf(__uint_as_float(rr[0]), __uint_as_float(rr[1])); }
;   if (__builtin_expect(!first && __all(pmax <= THRL), 1)) { alpha = 1.f; }
;   else { const float dl = first ? pmax : fmaxf(pmax, 0.f); m_ref += dl; alpha = first ? 1.f : __builtin_amdgcn_exp2f(-dl);
; #pragma unroll
;     for (int r = 0; r < 16; ++r) { p0[r] -= dl; p1[r] -= dl; } }
; #pragma unroll
;   for (int r = 0; r < 16; ++r) p0[r] = __builtin_amdgcn_exp2f(p0[r]);
; }
; __device__ __forceinline__ void finishSM(f32x16& p0, f32x16& p1, float alpha, float& l_reg, bf16x8& pa0, bf16x8& pa1, bf16x8& pa2, bf16x8& pa3) {
; #pragma unroll
;   for (int r = 0; r < 16; ++r) p1[r] = __builtin_amdgcn_exp2f(p1[r]);
; template <int D0> __device__ __forceinline__ void pv_one(f32x16& od, int vb, bf16x8 pa0, bf16x8 pa1, bf16x8 pa2, bf16x8 pa3) {
;   const s16x4 l0 = tr_read<v_rd_off(D0, 0, 0)>(vb), h0 = tr_read<v_rd_off(D0, 0, 1)>(vb), l1 = tr_read<v_rd_off(D0, 1, 0)>(vb), h1 = tr_read<v_rd_off(D0, 1, 1)>(vb);
;   const s16x4 l2 = tr_read<v_rd_off(D0, 2, 0)>(vb), h2 = tr_read<v_rd_off(D0, 2, 1)>(vb), l3 = tr_read<v_rd_off(D0, 3, 0)>(vb), h3 = tr_read<v_rd_off(D0, 3, 1)>(vb);
;   asm volatile("s_waitcnt lgkmcnt(0)" ::: "memory"); SBAR();
;     ...
;   od = __builtin_amdgcn_mfma_f32_32x32x16_bf16(pa0, PK(l0, h0), od, 0, 0, 0);
;   od = __builtin_amdgcn_mfma_f32_32x32x16_bf16(pa1, PK(l1, h1), od, 0, 0, 0);
;   od = __builtin_amdgcn_mfma_f32_32x32x16_bf16(pa2, PK(l2, h2), od, 0, 0, 0);
;   od = __builtin_amdgcn_mfma_f32_32x32x16_bf16(pa3, PK(l3, h3), od, 0, 0, 0);
;     ...
; }
; __device__ __forceinline__ void pv_d0(f32x16* o, int vb, bf16x8 pa0, bf16x8 pa1, bf16x8 pa2, bf16x8 pa3) {
;   pv_one<0>(o[0], vb, pa0, pa1, pa2, pa3); pv_one<1>(o[1], vb, pa0, pa1, pa2, pa3); pv_one<2>(o[2], vb, pa0, pa1, pa2, pa3); pv_one<3>(o[3], vb, pa0, pa1, pa2, pa3);
.Lat_back0:
	s_waitcnt lgkmcnt(12)
	v_mfma_f32_32x32x16_bf16 v[0:15], v[68:71], v[198:201], v[0:15]
	ds_read_b64_tr_b16 v[194:195], v172 offset:0x2600
	ds_read_b64_tr_b16 v[196:197], v172 offset:0x2e00
	v_exp_f32_e32 v96, v96
	v_exp_f32_e32 v97, v97
	v_exp_f32_e32 v98, v98
	s_waitcnt lgkmcnt(12)
	v_mfma_f32_32x32x16_bf16 v[48:63], v[68:71], v[202:205], v[48:63]
	ds_read_b64_tr_b16 v[198:199], v172 offset:0x3000
	ds_read_b64_tr_b16 v[200:201], v172 offset:0x3800
	v_exp_f32_e32 v99, v99
	v_exp_f32_e32 v100, v100
	v_exp_f32_e32 v101, v101
	s_waitcnt lgkmcnt(12)
	v_mfma_f32_32x32x16_bf16 v[32:47], v[68:71], v[206:209], v[32:47]
	ds_read_b64_tr_b16 v[202:203], v172 offset:0x3200
	ds_read_b64_tr_b16 v[204:205], v172 offset:0x3a00
	v_exp_f32_e32 v102, v102
	v_exp_f32_e32 v103, v103
	v_exp_f32_e32 v104, v104
	s_waitcnt lgkmcnt(12)
	v_mfma_f32_32x32x16_bf16 v[16:31], v[68:71], v[210:213], v[16:31]
	ds_read_b64_tr_b16 v[206:207], v172 offset:0x3400
	ds_read_b64_tr_b16 v[208:209], v172 offset:0x3c00
	v_exp_f32_e32 v105, v105
	v_exp_f32_e32 v106, v106
	v_exp_f32_e32 v107, v107
	s_waitcnt lgkmcnt(12)
	v_mfma_f32_32x32x16_bf16 v[0:15], v[72:75], v[182:185], v[0:15]
	ds_read_b64_tr_b16 v[210:211], v172 offset:0x3600
	ds_read_b64_tr_b16 v[212:213], v172 offset:0x3e00
	s_add_i32 s58, s52, 1
	s_and_b32 s58, s58, 3
	s_lshl_b32 s58, s58, 13
	v_add_u32_e32 v218, s58, v173
	ds_read_b128 v[182:185], v218 offset:49152
	v_exp_f32_e32 v108, v108
	v_exp_f32_e32 v109, v109
	v_exp_f32_e32 v110, v110
	s_waitcnt lgkmcnt(13)
	v_mfma_f32_32x32x16_bf16 v[48:63], v[72:75], v[186:189], v[48:63]
	ds_read_b128 v[186:189], v218 offset:53248
	v_exp_f32_e32 v111, v111
	v_exp_f32_e32 v236, v236
	v_exp_f32_e32 v237, v237
	s_waitcnt lgkmcnt(12)
	v_mfma_f32_32x32x16_bf16 v[32:47], v[72:75], v[190:193], v[32:47]
	v_add_u32_e32 v218, s58, v175
	ds_read_b128 v[190:193], v218 offset:49152
	v_exp_f32_e32 v238, v238
	v_exp_f32_e32 v239, v239
	v_exp_f32_e32 v240, v240
	s_waitcnt lgkmcnt(11)
	v_mfma_f32_32x32x16_bf16 v[16:31], v[72:75], v[194:197], v[16:31]
	ds_read_b128 v[194:197], v218 offset:53248
	v_exp_f32_e32 v241, v241
	v_exp_f32_e32 v242, v242
	v_exp_f32_e32 v243, v243
	s_waitcnt lgkmcnt(10)
	v_mfma_f32_32x32x16_bf16 v[0:15], v[76:79], v[198:201], v[0:15]
	v_add_u32_e32 v218, s58, v174
	ds_read_b128 v[198:201], v218 offset:49152
	v_exp_f32_e32 v244, v244
	v_exp_f32_e32 v245, v245
	s_waitcnt lgkmcnt(9)
	v_mfma_f32_32x32x16_bf16 v[48:63], v[76:79], v[202:205], v[48:63]
	ds_read_b128 v[202:205], v218 offset:53248
	v_exp_f32_e32 v246, v246
	v_exp_f32_e32 v247, v247
	s_waitcnt lgkmcnt(8)
	v_mfma_f32_32x32x16_bf16 v[32:47], v[76:79], v[206:209], v[32:47]
	v_add_u32_e32 v218, s58, v176
	ds_read_b128 v[206:209], v218 offset:49152
	v_exp_f32_e32 v248, v248
	v_exp_f32_e32 v249, v249
	s_waitcnt lgkmcnt(7)
	v_mfma_f32_32x32x16_bf16 v[16:31], v[76:79], v[210:213], v[16:31]
	ds_read_b128 v[210:213], v218 offset:53248
	v_exp_f32_e32 v250, v250
	v_exp_f32_e32 v251, v251
	s_cmp_lg_u32 s21, 0
	s_cbranch_scc1 .Lat_resc0
.Lat_rescback0:
	s_mov_b32 s21, 0
	s_lshl_b32 s59, s1, 14
	v_add_u32_e32 v172, s59, v177
	s_lshl_b32 s20, s2, 14
	s_add_i32 s20, s20, s79
	s_add_i32 s20, s20, s79
	s_add_i32 s58, s52, 4
	s_and_b32 s58, s58, 3
	s_lshl_b32 s58, s58, 13
	s_add_i32 s58, s58, s79
	s_add_i32 s58, s58, 0xc000
	s_waitcnt vmcnt(3)
	s_barrier
	s_waitcnt lgkmcnt(7)
	v_mfma_f32_32x32x16_bf16 v[64:79], v[182:185], v[124:127], v[128:143]
	ds_read_b64_tr_b16 v[182:183], v172 offset:0x0
	ds_read_b64_tr_b16 v[184:185], v172 offset:0x800
	v_add_f32_e32 v159, v96, v97
	v_cvt_pk_bf16_f32 v96, v96, v97
	v_add_f32_e32 v160, v98, v99
	v_cvt_pk_bf16_f32 v97, v98, v99
	v_add_f32_e32 v159, v100, v159
	v_add_f32_e32 v160, v101, v160
	v_cvt_pk_bf16_f32 v98, v100, v101
	s_waitcnt lgkmcnt(8)
	v_mfma_f32_32x32x16_bf16 v[80:95], v[186:189], v[124:127], v[128:143]
	ds_read_b64_tr_b16 v[186:187], v172 offset:0x200
	ds_read_b64_tr_b16 v[188:189], v172 offset:0xa00
	v_add_f32_e32 v159, v102, v159
	v_add_f32_e32 v160, v103, v160
	v_cvt_pk_bf16_f32 v99, v102, v103
	v_add_f32_e32 v159, v104, v159
	v_add_f32_e32 v160, v105, v160
	v_cvt_pk_bf16_f32 v100, v104, v105
	v_add_f32_e32 v159, v106, v159
	s_waitcnt lgkmcnt(9)
	v_mfma_f32_32x32x16_bf16 v[64:79], v[190:193], v[120:123], v[64:79]
	ds_read_b64_tr_b16 v[190:191], v172 offset:0x400
	ds_read_b64_tr_b16 v[192:193], v172 offset:0xc00
	v_add_f32_e32 v160, v107, v160
	v_cvt_pk_bf16_f32 v101, v106, v107
	v_add_f32_e32 v159, v108, v159
	v_add_f32_e32 v160, v109, v160
	v_cvt_pk_bf16_f32 v102, v108, v109
	v_add_f32_e32 v159, v110, v159
	v_add_f32_e32 v160, v111, v160
	s_waitcnt lgkmcnt(10)
	v_mfma_f32_32x32x16_bf16 v[80:95], v[194:197], v[120:123], v[80:95]
	ds_read_b64_tr_b16 v[194:195], v172 offset:0x600
	ds_read_b64_tr_b16 v[196:197], v172 offset:0xe00
	s_mov_b32 m0, s20
	s_nop 0
	global_load_lds_dwordx4 v233, s[24:25]
	s_add_i32 m0, m0, 0x400
	s_nop 0
	global_load_lds_dwordx4 v234, s[24:25]
	s_mov_b32 m0, s58
	s_nop 0
	global_load_lds_dwordx4 v232, s[24:25]
	s_add_u32 s24, s24, 0x10000
	s_addc_u32 s25, s25, 0
	v_cvt_pk_bf16_f32 v103, v110, v111
	v_add_f32_e32 v159, v236, v159
	v_add_f32_e32 v160, v237, v160
	v_cvt_pk_bf16_f32 v104, v236, v237
	v_add_f32_e32 v159, v238, v159
	v_add_f32_e32 v160, v239, v160
	v_cvt_pk_bf16_f32 v105, v238, v239
	s_waitcnt lgkmcnt(11)
; #define SBAR() __builtin_amdgcn_sched_barrier(0)
; __device__ __forceinline__ void partialSM(f32x16& p0, f32x16& p1, float& m_ref, float& alpha, bool first) {
;   constexpr float THRL = THR * 1.4426950408889634f;
;   float pmax = p0[0];
; #pragma unroll
;   for (int r = 1; r < 16; ++r) pmax = fmaxf(pmax, p0[r]);
; #pragma unroll
;   for (int r = 0; r < 16; ++r) pmax = fmaxf(pmax, p1[r]);
;   { auto rr = __builtin_amdgcn_permlane32_swap(__float_as_uint(pmax), __float_as_uint(pmax), false, false);
;     pmax = fmaxf(__uint_as_float(rr[0]), __uint_as_float(rr[1])); }
;   if (__builtin_expect(!first && __all(pmax <= THRL), 1)) { alpha = 1.f; }
;   else { const float dl = first ? pmax : fmaxf(pmax, 0.f); m_ref += dl; alpha = first ? 1.f : __builtin_amdgcn_exp2f(-dl);
; #pragma unroll
;     for (int r = 0; r < 16; ++r) { p0[r] -= dl; p1[r] -= dl; } }
; #pragma unroll
;   for (int r = 0; r < 16; ++r) p0[r] = __builtin_amdgcn_exp2f(p0[r]);
; }
; __device__ __forceinline__ void finishSM(f32x16& p0, f32x16& p1, float alpha, float& l_reg, bf16x8& pa0, bf16x8& pa1, bf16x8& pa2, bf16x8& pa3) {
; #pragma unroll
;   for (int r = 0; r < 16; ++r) p1[r] = __builtin_amdgcn_exp2f(p1[r]);
; template <int D0> __device__ __forceinline__ void pv_one(f32x16& od, int vb, bf16x8 pa0, bf16x8 pa1, bf16x8 pa2, bf16x8 pa3) {
;   const s16x4 l0 = tr_read<v_rd_off(D0, 0, 0)>(vb), h0 = tr_read<v_rd_off(D0, 0, 1)>(vb), l1 = tr_read<v_rd_off(D0, 1, 0)>(vb), h1 = tr_read<v_rd_off(D0, 1, 1)>(vb);
;   const s16x4 l2 = tr_read<v_rd_off(D0, 2, 0)>(vb), h2 = tr_read<v_rd_off(D0, 2, 1)>(vb), l3 = tr_read<v_rd_off(D0, 3, 0)>(vb), h3 = tr_read<v_rd_off(D0, 3, 1)>(vb);
;   asm volatile("s_waitcnt lgkmcnt(0)" ::: "memory"); SBAR();
;     ...
;   od = __builtin_amdgcn_mfma_f32_32x32x16_bf16(pa0, PK(l0, h0), od, 0, 0, 0);
;   od = __builtin_amdgcn_mfma_f32_32x32x16_bf16(pa1, PK(l1, h1), od, 0, 0, 0);
;   od = __builtin_amdgcn_mfma_f32_32x32x16_bf16(pa2, PK(l2, h2), od, 0, 0, 0);
;   od = __builtin_amdgcn_mfma_f32_32x32x16_bf16(pa3, PK(l3, h3), od, 0, 0, 0);
;     ...
; }
; __device__ __forceinline__ void pv_d0(f32x16* o, int vb, bf16x8 pa0, bf16x8 pa1, bf16x8 pa2, bf16x8 pa3) {
;   pv_one<0>(o[0], vb, pa0, pa1, pa2, pa3); pv_one<1>(o[1], vb, pa0, pa1, pa2, pa3); pv_one<2>(o[2], vb, pa0, pa1, pa2, pa3); pv_one<3>(o[3], vb, pa0, pa1, pa2, pa3);
	v_mfma_f32_32x32x16_bf16 v[64:79], v[198:201], v[116:119], v[64:79]
	ds_read_b64_tr_b16 v[198:199], v172 offset:0x1000
	ds_read_b64_tr_b16 v[200:201], v172 offset:0x1800
	v_add_f32_e32 v159, v240, v159
	v_add_f32_e32 v160, v241, v160
	v_cvt_pk_bf16_f32 v106, v240, v241
	v_add_f32_e32 v159, v242, v159
	v_add_f32_e32 v160, v243, v160
	v_cvt_pk_bf16_f32 v107, v242, v243
	v_add_f32_e32 v159, v244, v159
	s_waitcnt lgkmcnt(12)
	v_mfma_f32_32x32x16_bf16 v[80:95], v[202:205], v[116:119], v[80:95]
	ds_read_b64_tr_b16 v[202:203], v172 offset:0x1200
	ds_read_b64_tr_b16 v[204:205], v172 offset:0x1a00
	v_add_f32_e32 v160, v245, v160
	v_cvt_pk_bf16_f32 v108, v244, v245
	v_add_f32_e32 v159, v246, v159
	v_add_f32_e32 v160, v247, v160
	v_cvt_pk_bf16_f32 v109, v246, v247
	v_add_f32_e32 v159, v248, v159
	v_add_f32_e32 v160, v249, v160
	s_waitcnt lgkmcnt(13)
	v_mfma_f32_32x32x16_bf16 v[64:79], v[206:209], v[112:115], v[64:79]
	ds_read_b64_tr_b16 v[206:207], v172 offset:0x1400
	ds_read_b64_tr_b16 v[208:209], v172 offset:0x1c00
	v_cvt_pk_bf16_f32 v110, v248, v249
	v_add_f32_e32 v159, v250, v159
	v_add_f32_e32 v160, v251, v160
	v_cvt_pk_bf16_f32 v111, v250, v251
	v_add_f32_e32 v159, v159, v160
	v_fma_f32 v167, v167, v158, v159
	s_waitcnt lgkmcnt(14)
	v_mfma_f32_32x32x16_bf16 v[80:95], v[210:213], v[112:115], v[80:95]
	s_waitcnt lgkmcnt(12)
	v_mfma_f32_32x32x16_bf16 v[0:15], v[96:99], v[182:185], v[0:15]
	ds_read_b64_tr_b16 v[210:211], v172 offset:0x1600
	ds_read_b64_tr_b16 v[212:213], v172 offset:0x1e00
	v_max3_f32 v161, v64, v65, v66
	v_max3_f32 v161, v161, v67, v68
	v_max3_f32 v161, v161, v69, v70
	v_max3_f32 v161, v161, v71, v72
	s_waitcnt lgkmcnt(12)
	v_mfma_f32_32x32x16_bf16 v[48:63], v[96:99], v[186:189], v[48:63]
	ds_read_b64_tr_b16 v[182:183], v172 offset:0x2000
	ds_read_b64_tr_b16 v[184:185], v172 offset:0x2800
	v_max3_f32 v161, v161, v73, v74
	v_max3_f32 v161, v161, v75, v76
	v_max3_f32 v161, v161, v77, v78
	v_max_f32_e32 v161, v161, v79
	s_waitcnt lgkmcnt(12)
	v_mfma_f32_32x32x16_bf16 v[32:47], v[96:99], v[190:193], v[32:47]
	ds_read_b64_tr_b16 v[186:187], v172 offset:0x2200
	ds_read_b64_tr_b16 v[188:189], v172 offset:0x2a00
	v_max3_f32 v216, v80, v81, v82
	v_max3_f32 v216, v216, v83, v84
	v_max3_f32 v216, v216, v85, v86
	v_max3_f32 v216, v216, v87, v88
	s_waitcnt lgkmcnt(12)
	v_mfma_f32_32x32x16_bf16 v[16:31], v[96:99], v[194:197], v[16:31]
	ds_read_b64_tr_b16 v[190:191], v172 offset:0x2400
	ds_read_b64_tr_b16 v[192:193], v172 offset:0x2c00
	v_max3_f32 v216, v216, v89, v90
	v_max3_f32 v216, v216, v91, v92
	v_max3_f32 v216, v216, v93, v94
	v_max_f32_e32 v216, v216, v95
	v_max_f32_e32 v161, v161, v216
	v_cmp_ge_f32_e32 vcc, s66, v161
	s_cmp_eq_u64 vcc, exec
	s_cbranch_scc0 .Lat_rare1
	v_mov_b32_e32 v235, 1.0
.Lat_back1:
	s_waitcnt lgkmcnt(12)
	v_mfma_f32_32x32x16_bf16 v[0:15], v[100:103], v[198:201], v[0:15]
	ds_read_b64_tr_b16 v[194:195], v172 offset:0x2600
	ds_read_b64_tr_b16 v[196:197], v172 offset:0x2e00
	v_exp_f32_e32 v64, v64
	v_exp_f32_e32 v65, v65
	v_exp_f32_e32 v66, v66
	s_waitcnt lgkmcnt(12)
	v_mfma_f32_32x32x16_bf16 v[48:63], v[100:103], v[202:205], v[48:63]
	ds_read_b64_tr_b16 v[198:199], v172 offset:0x3000
	ds_read_b64_tr_b16 v[200:201], v172 offset:0x3800
	v_exp_f32_e32 v67, v67
	v_exp_f32_e32 v68, v68
	v_exp_f32_e32 v69, v69
	s_waitcnt lgkmcnt(12)
	v_mfma_f32_32x32x16_bf16 v[32:47], v[100:103], v[206:209], v[32:47]
	ds_read_b64_tr_b16 v[202:203], v172 offset:0x3200
	ds_read_b64_tr_b16 v[204:205], v172 offset:0x3a00
	v_exp_f32_e32 v70, v70
	v_exp_f32_e32 v71, v71
	v_exp_f32_e32 v72, v72
	s_waitcnt lgkmcnt(12)
	v_mfma_f32_32x32x16_bf16 v[16:31], v[100:103], v[210:213], v[16:31]
	ds_read_b64_tr_b16 v[206:207], v172 offset:0x3400
	ds_read_b64_tr_b16 v[208:209], v172 offset:0x3c00
	v_exp_f32_e32 v73, v73
	v_exp_f32_e32 v74, v74
	v_exp_f32_e32 v75, v75
	s_waitcnt lgkmcnt(12)
	v_mfma_f32_32x32x16_bf16 v[0:15], v[104:107], v[182:185], v[0:15]
	ds_read_b64_tr_b16 v[210:211], v172 offset:0x3600
	ds_read_b64_tr_b16 v[212:213], v172 offset:0x3e00
	s_add_i32 s58, s52, 2
	s_and_b32 s58, s58, 3
	s_lshl_b32 s58, s58, 13
	v_add_u32_e32 v218, s58, v173
	ds_read_b128 v[182:185], v218 offset:49152
	v_exp_f32_e32 v76, v76
	v_exp_f32_e32 v77, v77
	v_exp_f32_e32 v78, v78
	s_waitcnt lgkmcnt(13)
	v_mfma_f32_32x32x16_bf16 v[48:63], v[104:107], v[186:189], v[48:63]
	ds_read_b128 v[186:189], v218 offset:53248
	v_exp_f32_e32 v79, v79
	v_exp_f32_e32 v80, v80
	v_exp_f32_e32 v81, v81
	s_waitcnt lgkmcnt(12)
	v_mfma_f32_32x32x16_bf16 v[32:47], v[104:107], v[190:193], v[32:47]
	v_add_u32_e32 v218, s58, v175
	ds_read_b128 v[190:193], v218 offset:49152
	v_exp_f32_e32 v82, v82
	v_exp_f32_e32 v83, v83
	v_exp_f32_e32 v84, v84
	s_waitcnt lgkmcnt(11)
	v_mfma_f32_32x32x16_bf16 v[16:31], v[104:107], v[194:197], v[16:31]
	ds_read_b128 v[194:197], v218 offset:53248
	v_exp_f32_e32 v85, v85
	v_exp_f32_e32 v86, v86
	v_exp_f32_e32 v87, v87
	s_waitcnt lgkmcnt(10)
	v_mfma_f32_32x32x16_bf16 v[0:15], v[108:111], v[198:201], v[0:15]
	v_add_u32_e32 v218, s58, v174
	ds_read_b128 v[198:201], v218 offset:49152
	v_exp_f32_e32 v88, v88
	v_exp_f32_e32 v89, v89
	s_waitcnt lgkmcnt(9)
	v_mfma_f32_32x32x16_bf16 v[48:63], v[108:111], v[202:205], v[48:63]
	ds_read_b128 v[202:205], v218 offset:53248
	v_exp_f32_e32 v90, v90
	v_exp_f32_e32 v91, v91
	s_waitcnt lgkmcnt(8)
	v_mfma_f32_32x32x16_bf16 v[32:47], v[108:111], v[206:209], v[32:47]
	v_add_u32_e32 v218, s58, v176
	ds_read_b128 v[206:209], v218 offset:49152
	v_exp_f32_e32 v92, v92
	v_exp_f32_e32 v93, v93
	s_waitcnt lgkmcnt(7)
	v_mfma_f32_32x32x16_bf16 v[16:31], v[108:111], v[210:213], v[16:31]
	ds_read_b128 v[210:213], v218 offset:53248
	v_exp_f32_e32 v94, v94
	v_exp_f32_e32 v95, v95
	s_cmp_lg_u32 s21, 0
	s_cbranch_scc1 .Lat_resc1

; __device__ __forceinline__ void partialSM(f32x16& p0, f32x16& p1, float& m_ref, float& alpha, bool first) {
;   constexpr float THRL = THR * 1.4426950408889634f;
;   float pmax = p0[0];
; #pragma unroll
;   for (int r = 1; r < 16; ++r) pmax = fmaxf(pmax, p0[r]);
; #pragma unroll
;   for (int r = 0; r < 16; ++r) pmax = fmaxf(pmax, p1[r]);
;   { auto rr = __builtin_amdgcn_permlane32_swap(__float_as_uint(pmax), __float_as_uint(pmax), false, false);
;     pmax = fmaxf(__uint_as_float(rr[0]), __uint_as_float(rr[1])); }
;   if (__builtin_expect(!first && __all(pmax <= THRL), 1)) { alpha = 1.f; }
;   else { const float dl = first ? pmax : fmaxf(pmax, 0.f); m_ref += dl; alpha = first ? 1.f : __builtin_amdgcn_exp2f(-dl);
; #pragma unroll
;     for (int r = 0; r < 16; ++r) { p0[r] -= dl; p1[r] -= dl; } }
; #pragma unroll
;   for (int r = 0; r < 16; ++r) p0[r] = __builtin_amdgcn_exp2f(p0[r]);
; }
; __device__ __forceinline__ void finishSM(f32x16& p0, f32x16& p1, float alpha, float& l_reg, bf16x8& pa0, bf16x8& pa1, bf16x8& pa2, bf16x8& pa3) {
; #pragma unroll
;   for (int r = 0; r < 16; ++r) p1[r] = __builtin_amdgcn_exp2f(p1[r]);
;   float ps = 0;
; #pragma unroll
;   for (int r = 0; r < 16; ++r) ps += p0[r];
; #pragma unroll
;   for (int r = 0; r < 16; ++r) ps += p1[r];
;   { auto rr = __builtin_amdgcn_permlane32_swap(__float_as_uint(ps), __float_as_uint(ps), false, false);
;     ps = __uint_as_float(rr[0]) + __uint_as_float(rr[1]); }
;   l_reg = l_reg * alpha + ps;
;     ...
;   PK4(p0, 0, pa0); PK4(p0, 8, pa1); PK4(p1, 0, pa2); PK4(p1, 8, pa3);
;     ...
; }
; __device__ __forceinline__ void qkt(f32x16& p0, f32x16& p1, const char* Ks, const bf16x8* qr, int r32, int hi, float m_ref) {
; #pragma unroll
;   for (int r = 0; r < 16; ++r) { p0[r] = -m_ref; p1[r] = -m_ref; }
; __device__ __forceinline__ void attn_unit(const bf16_t* __restrict__ Qb, const bf16_t* __restrict__ Kh, const bf16_t* __restrict__ Vh, int seq, char* lds,
;                                           int mode, float* scratch, float lam, float gscale, const float* __restrict__ subg, bf16_t* outp) {
;     ...
;   for (int j = 1; j + 1 < NT; j += 2) {
;     SBAR(); qkt(pB0, pB1, K_lds + bc * SHM_K, qr, r32, hi, m_reg);
;     finishSM(pA0, pA1, alA, l_reg, pa0, pa1, pa2, pa3); SBAR();
;     SLOAD(SO, (j + 2) * KVBLK); SBAR();
;     pv_d0(o, vb0 + bp * SHM_V, pa0, pa1, pa2, pa3); partialSM(pB0, pB1, m_reg, alB, false);
.Lg1_loop:
	s_barrier
	s_mov_b32 m0, s20
	s_nop 0
	global_load_lds_dwordx4 v233, s[24:25]
	s_add_i32 m0, m0, 0x400
	s_nop 0
	global_load_lds_dwordx4 v234, s[24:25]
	s_mov_b32 m0, s58
	s_nop 0
	global_load_lds_dwordx4 v232, s[24:25]
	s_add_u32 s24, s24, 0x10000
	s_addc_u32 s25, s25, 0
	s_waitcnt lgkmcnt(7)
	v_mfma_f32_32x32x16_bf16 v[96:111], v[182:185], v[124:127], v[128:143]
	ds_read_b64_tr_b16 v[182:183], v172 offset:0x0
	ds_read_b64_tr_b16 v[184:185], v172 offset:0x800
	v_add_f32_e32 v159, v64, v65
	v_cvt_pk_bf16_f32 v64, v64, v65
	v_add_f32_e32 v160, v66, v67
	v_cvt_pk_bf16_f32 v65, v66, v67
	v_add_f32_e32 v159, v68, v159
	v_add_f32_e32 v160, v69, v160
	v_cvt_pk_bf16_f32 v66, v68, v69
	s_waitcnt lgkmcnt(8)
	v_mfma_f32_32x32x16_bf16 v[236:251], v[186:189], v[124:127], v[128:143]
	ds_read_b64_tr_b16 v[186:187], v172 offset:0x200
	ds_read_b64_tr_b16 v[188:189], v172 offset:0xa00
	v_add_f32_e32 v159, v70, v159
	v_add_f32_e32 v160, v71, v160
	v_cvt_pk_bf16_f32 v67, v70, v71
	v_add_f32_e32 v159, v72, v159
	v_add_f32_e32 v160, v73, v160
	v_cvt_pk_bf16_f32 v68, v72, v73
	v_add_f32_e32 v159, v74, v159
	s_waitcnt lgkmcnt(9)
	v_mfma_f32_32x32x16_bf16 v[96:111], v[190:193], v[120:123], v[96:111]
	ds_read_b64_tr_b16 v[190:191], v172 offset:0x400
	ds_read_b64_tr_b16 v[192:193], v172 offset:0xc00
	v_add_f32_e32 v160, v75, v160
	v_cvt_pk_bf16_f32 v69, v74, v75
	v_add_f32_e32 v159, v76, v159
	v_add_f32_e32 v160, v77, v160
	v_cvt_pk_bf16_f32 v70, v76, v77
	v_add_f32_e32 v159, v78, v159
	v_add_f32_e32 v160, v79, v160
	s_waitcnt lgkmcnt(10)
	v_mfma_f32_32x32x16_bf16 v[236:251], v[194:197], v[120:123], v[236:251]
	ds_read_b64_tr_b16 v[194:195], v172 offset:0x600
	ds_read_b64_tr_b16 v[196:197], v172 offset:0xe00
	v_cvt_pk_bf16_f32 v71, v78, v79
	v_add_f32_e32 v159, v80, v159
	v_add_f32_e32 v160, v81, v160
	v_cvt_pk_bf16_f32 v72, v80, v81
	v_add_f32_e32 v159, v82, v159
	v_add_f32_e32 v160, v83, v160
	v_cvt_pk_bf16_f32 v73, v82, v83
	s_waitcnt lgkmcnt(11)
	v_mfma_f32_32x32x16_bf16 v[96:111], v[198:201], v[116:119], v[96:111]
	ds_read_b64_tr_b16 v[198:199], v172 offset:0x1000
	ds_read_b64_tr_b16 v[200:201], v172 offset:0x1800
	v_add_f32_e32 v159, v84, v159
	v_add_f32_e32 v160, v85, v160
	v_cvt_pk_bf16_f32 v74, v84, v85
	v_add_f32_e32 v159, v86, v159
	v_add_f32_e32 v160, v87, v160
	v_cvt_pk_bf16_f32 v75, v86, v87
	v_add_f32_e32 v159, v88, v159
	s_waitcnt lgkmcnt(12)
	v_mfma_f32_32x32x16_bf16 v[236:251], v[202:205], v[116:119], v[236:251]
	ds_read_b64_tr_b16 v[202:203], v172 offset:0x1200
	ds_read_b64_tr_b16 v[204:205], v172 offset:0x1a00
	v_add_f32_e32 v160, v89, v160
	v_cvt_pk_bf16_f32 v76, v88, v89
	v_add_f32_e32 v159, v90, v159
	v_add_f32_e32 v160, v91, v160
	v_cvt_pk_bf16_f32 v77, v90, v91
	v_add_f32_e32 v159, v92, v159
	v_add_f32_e32 v160, v93, v160
	s_waitcnt lgkmcnt(13)
	v_mfma_f32_32x32x16_bf16 v[96:111], v[206:209], v[112:115], v[96:111]
	ds_read_b64_tr_b16 v[206:207], v172 offset:0x1400
	ds_read_b64_tr_b16 v[208:209], v172 offset:0x1c00
	v_cvt_pk_bf16_f32 v78, v92, v93
	v_add_f32_e32 v159, v94, v159
	v_add_f32_e32 v160, v95, v160
	v_cvt_pk_bf16_f32 v79, v94, v95
	v_add_f32_e32 v159, v159, v160
	v_fma_f32 v167, v167, v235, v159
	s_waitcnt lgkmcnt(14)
	v_mfma_f32_32x32x16_bf16 v[236:251], v[210:213], v[112:115], v[236:251]
	s_waitcnt lgkmcnt(12)
	v_mfma_f32_32x32x16_bf16 v[0:15], v[64:67], v[182:185], v[0:15]
	ds_read_b64_tr_b16 v[210:211], v172 offset:0x1600
	ds_read_b64_tr_b16 v[212:213], v172 offset:0x1e00
	v_max3_f32 v161, v96, v97, v98
	v_max3_f32 v161, v161, v99, v100
	v_max3_f32 v161, v161, v101, v102
	v_max3_f32 v161, v161, v103, v104
	s_waitcnt lgkmcnt(12)
	v_mfma_f32_32x32x16_bf16 v[48:63], v[64:67], v[186:189], v[48:63]
	ds_read_b64_tr_b16 v[182:183], v172 offset:0x2000
	ds_read_b64_tr_b16 v[184:185], v172 offset:0x2800
	v_max3_f32 v161, v161, v105, v106
	v_max3_f32 v161, v161, v107, v108
	v_max3_f32 v161, v161, v109, v110
	v_max_f32_e32 v161, v161, v111
	s_waitcnt lgkmcnt(12)
	v_mfma_f32_32x32x16_bf16 v[32:47], v[64:67], v[190:193], v[32:47]
	ds_read_b64_tr_b16 v[186:187], v172 offset:0x2200
	ds_read_b64_tr_b16 v[188:189], v172 offset:0x2a00
	v_max3_f32 v216, v236, v237, v238
	v_max3_f32 v216, v216, v239, v240
	v_max3_f32 v216, v216, v241, v242
	v_max3_f32 v216, v216, v243, v244
	s_waitcnt lgkmcnt(12)
	v_mfma_f32_32x32x16_bf16 v[16:31], v[64:67], v[194:197], v[16:31]
	ds_read_b64_tr_b16 v[190:191], v172 offset:0x2400
	ds_read_b64_tr_b16 v[192:193], v172 offset:0x2c00
	v_max3_f32 v216, v216, v245, v246
	v_max3_f32 v216, v216, v247, v248
	v_max3_f32 v216, v216, v249, v250
	v_max_f32_e32 v216, v216, v251
	v_max_f32_e32 v161, v161, v216
	v_cmp_ge_f32_e32 vcc, s66, v161
	s_cmp_eq_u64 vcc, exec
	s_cbranch_scc0 .Lg1_rare0
	v_mov_b32_e32 v158, 1.0

; __device__ __forceinline__ void partialSM(f32x16& p0, f32x16& p1, float& m_ref, float& alpha, bool first) {
;   constexpr float THRL = THR * 1.4426950408889634f;
;   float pmax = p0[0];
; #pragma unroll
;   for (int r = 1; r < 16; ++r) pmax = fmaxf(pmax, p0[r]);
; #pragma unroll
;   for (int r = 0; r < 16; ++r) pmax = fmaxf(pmax, p1[r]);
;   { auto rr = __builtin_amdgcn_permlane32_swap(__float_as_uint(pmax), __float_as_uint(pmax), false, false);
;     pmax = fmaxf(__uint_as_float(rr[0]), __uint_as_float(rr[1])); }
;   if (__builtin_expect(!first && __all(pmax <= THRL), 1)) { alpha = 1.f; }
;   else { const float dl = first ? pmax : fmaxf(pmax, 0.f); m_ref += dl; alpha = first ? 1.f : __builtin_amdgcn_exp2f(-dl);
; #pragma unroll
;     for (int r = 0; r < 16; ++r) { p0[r] -= dl; p1[r] -= dl; } }
; #pragma unroll
;   for (int r = 0; r < 16; ++r) p0[r] = __builtin_amdgcn_exp2f(p0[r]);
; }
; __device__ __forceinline__ void finishSM(f32x16& p0, f32x16& p1, float alpha, float& l_reg, bf16x8& pa0, bf16x8& pa1, bf16x8& pa2, bf16x8& pa3) {
; #pragma unroll
;   for (int r = 0; r < 16; ++r) p1[r] = __builtin_amdgcn_exp2f(p1[r]);
;   float ps = 0;
; #pragma unroll
;   for (int r = 0; r < 16; ++r) ps += p0[r];
; #pragma unroll
;   for (int r = 0; r < 16; ++r) ps += p1[r];
;   { auto rr = __builtin_amdgcn_permlane32_swap(__float_as_uint(ps), __float_as_uint(ps), false, false);
;     ps = __uint_as_float(rr[0]) + __uint_as_float(rr[1]); }
;   l_reg = l_reg * alpha + ps;
;     ...
;   PK4(p0, 0, pa0); PK4(p0, 8, pa1); PK4(p1, 0, pa2); PK4(p1, 8, pa3);
;     ...
; }
; __device__ __forceinline__ void qkt(f32x16& p0, f32x16& p1, const char* Ks, const bf16x8* qr, int r32, int hi, float m_ref) {
; #pragma unroll
;   for (int r = 0; r < 16; ++r) { p0[r] = -m_ref; p1[r] = -m_ref; }
; #pragma unroll
; __device__ __forceinline__ void attn_unit(const bf16_t* __restrict__ Qb, const bf16_t* __restrict__ Kh, const bf16_t* __restrict__ Vh, int seq, char* lds,
;                                           int mode, float* scratch, float lam, float gscale, const float* __restrict__ subg, bf16_t* outp) {
;     ...
;     SBAR(); qkt(pA0, pA1, K_lds + bc * SHM_K, qr, r32, hi, m_reg);
;     finishSM(pB0, pB1, alB, l_reg, pa0, pa1, pa2, pa3); SBAR();
;     if (j + 3 < NT) SLOAD(SE, (j + 3) * KVBLK); SBAR();
;     pv_d0(o, vb0 + bp * SHM_V, pa0, pa1, pa2, pa3); partialSM(pA0, pA1, m_reg, alA, false);
.Lg1_rescback0:
	s_mov_b32 s21, 0
	s_lshl_b32 s59, s1, 14
	v_add_u32_e32 v172, s59, v177
	s_lshl_b32 s20, s2, 14
	s_add_i32 s20, s20, s79
	s_add_i32 s20, s20, s79
	s_add_i32 s58, s52, 4
	s_and_b32 s58, s58, 3
	s_lshl_b32 s58, s58, 13
	s_add_i32 s58, s58, s79
	s_add_i32 s58, s58, 0xc000
	s_waitcnt vmcnt(3)
	s_barrier
	s_mov_b32 m0, s20
	s_nop 0
	global_load_lds_dwordx4 v233, s[24:25]
	s_add_i32 m0, m0, 0x400
	s_nop 0
	global_load_lds_dwordx4 v234, s[24:25]
	s_mov_b32 m0, s58
	s_nop 0
	global_load_lds_dwordx4 v232, s[24:25]
	s_add_u32 s24, s24, 0x10000
	s_addc_u32 s25, s25, 0
	s_waitcnt lgkmcnt(7)
	v_mfma_f32_32x32x16_bf16 v[64:79], v[182:185], v[124:127], v[128:143]
	ds_read_b64_tr_b16 v[182:183], v172 offset:0x0
	ds_read_b64_tr_b16 v[184:185], v172 offset:0x800
	v_add_f32_e32 v159, v96, v97
	v_cvt_pk_bf16_f32 v96, v96, v97
	v_add_f32_e32 v160, v98, v99
	v_cvt_pk_bf16_f32 v97, v98, v99
	v_add_f32_e32 v159, v100, v159
	v_add_f32_e32 v160, v101, v160
	v_cvt_pk_bf16_f32 v98, v100, v101
	s_waitcnt lgkmcnt(8)
	v_mfma_f32_32x32x16_bf16 v[80:95], v[186:189], v[124:127], v[128:143]
	ds_read_b64_tr_b16 v[186:187], v172 offset:0x200
	ds_read_b64_tr_b16 v[188:189], v172 offset:0xa00
	v_add_f32_e32 v159, v102, v159
	v_add_f32_e32 v160, v103, v160
	v_cvt_pk_bf16_f32 v99, v102, v103
	v_add_f32_e32 v159, v104, v159
	v_add_f32_e32 v160, v105, v160
	v_cvt_pk_bf16_f32 v100, v104, v105
	v_add_f32_e32 v159, v106, v159
	s_waitcnt lgkmcnt(9)
	v_mfma_f32_32x32x16_bf16 v[64:79], v[190:193], v[120:123], v[64:79]
	ds_read_b64_tr_b16 v[190:191], v172 offset:0x400
	ds_read_b64_tr_b16 v[192:193], v172 offset:0xc00
	v_add_f32_e32 v160, v107, v160
	v_cvt_pk_bf16_f32 v101, v106, v107
	v_add_f32_e32 v159, v108, v159
	v_add_f32_e32 v160, v109, v160
	v_cvt_pk_bf16_f32 v102, v108, v109
	v_add_f32_e32 v159, v110, v159
	v_add_f32_e32 v160, v111, v160
	s_waitcnt lgkmcnt(10)
	v_mfma_f32_32x32x16_bf16 v[80:95], v[194:197], v[120:123], v[80:95]
	ds_read_b64_tr_b16 v[194:195], v172 offset:0x600
	ds_read_b64_tr_b16 v[196:197], v172 offset:0xe00
	v_cvt_pk_bf16_f32 v103, v110, v111
	v_add_f32_e32 v159, v236, v159
	v_add_f32_e32 v160, v237, v160
	v_cvt_pk_bf16_f32 v104, v236, v237
	v_add_f32_e32 v159, v238, v159
	v_add_f32_e32 v160, v239, v160
	v_cvt_pk_bf16_f32 v105, v238, v239
	s_waitcnt lgkmcnt(11)
	v_mfma_f32_32x32x16_bf16 v[64:79], v[198:201], v[116:119], v[64:79]
	ds_read_b64_tr_b16 v[198:199], v172 offset:0x1000
	ds_read_b64_tr_b16 v[200:201], v172 offset:0x1800
	v_add_f32_e32 v159, v240, v159
	v_add_f32_e32 v160, v241, v160
	v_cvt_pk_bf16_f32 v106, v240, v241
	v_add_f32_e32 v159, v242, v159
	v_add_f32_e32 v160, v243, v160
	v_cvt_pk_bf16_f32 v107, v242, v243
	v_add_f32_e32 v159, v244, v159
	s_waitcnt lgkmcnt(12)
	v_mfma_f32_32x32x16_bf16 v[80:95], v[202:205], v[116:119], v[80:95]
	ds_read_b64_tr_b16 v[202:203], v172 offset:0x1200
	ds_read_b64_tr_b16 v[204:205], v172 offset:0x1a00
	v_add_f32_e32 v160, v245, v160
	v_cvt_pk_bf16_f32 v108, v244, v245
	v_add_f32_e32 v159, v246, v159
	v_add_f32_e32 v160, v247, v160
	v_cvt_pk_bf16_f32 v109, v246, v247
	v_add_f32_e32 v159, v248, v159
	v_add_f32_e32 v160, v249, v160
	s_waitcnt lgkmcnt(13)
	v_mfma_f32_32x32x16_bf16 v[64:79], v[206:209], v[112:115], v[64:79]
	ds_read_b64_tr_b16 v[206:207], v172 offset:0x1400
	ds_read_b64_tr_b16 v[208:209], v172 offset:0x1c00
	v_cvt_pk_bf16_f32 v110, v248, v249
	v_add_f32_e32 v159, v250, v159
	v_add_f32_e32 v160, v251, v160
	v_cvt_pk_bf16_f32 v111, v250, v251
	v_add_f32_e32 v159, v159, v160
	v_fma_f32 v167, v167, v158, v159
	s_waitcnt lgkmcnt(14)
	v_mfma_f32_32x32x16_bf16 v[80:95], v[210:213], v[112:115], v[80:95]
	s_waitcnt lgkmcnt(12)
	v_mfma_f32_32x32x16_bf16 v[0:15], v[96:99], v[182:185], v[0:15]
	ds_read_b64_tr_b16 v[210:211], v172 offset:0x1600
	ds_read_b64_tr_b16 v[212:213], v172 offset:0x1e00
	v_max3_f32 v161, v64, v65, v66
	v_max3_f32 v161, v161, v67, v68
	v_max3_f32 v161, v161, v69, v70
	v_max3_f32 v161, v161, v71, v72
	s_waitcnt lgkmcnt(12)
	v_mfma_f32_32x32x16_bf16 v[48:63], v[96:99], v[186:189], v[48:63]
	ds_read_b64_tr_b16 v[182:183], v172 offset:0x2000
	ds_read_b64_tr_b16 v[184:185], v172 offset:0x2800
	v_max3_f32 v161, v161, v73, v74
	v_max3_f32 v161, v161, v75, v76
	v_max3_f32 v161, v161, v77, v78
	v_max_f32_e32 v161, v161, v79
	s_waitcnt lgkmcnt(12)
	v_mfma_f32_32x32x16_bf16 v[32:47], v[96:99], v[190:193], v[32:47]
	ds_read_b64_tr_b16 v[186:187], v172 offset:0x2200
	ds_read_b64_tr_b16 v[188:189], v172 offset:0x2a00
	v_max3_f32 v216, v80, v81, v82
	v_max3_f32 v216, v216, v83, v84
	v_max3_f32 v216, v216, v85, v86
	v_max3_f32 v216, v216, v87, v88
	s_waitcnt lgkmcnt(12)
	v_mfma_f32_32x32x16_bf16 v[16:31], v[96:99], v[194:197], v[16:31]
	ds_read_b64_tr_b16 v[190:191], v172 offset:0x2400
	ds_read_b64_tr_b16 v[192:193], v172 offset:0x2c00
	v_max3_f32 v216, v216, v89, v90
	v_max3_f32 v216, v216, v91, v92
	v_max3_f32 v216, v216, v93, v94
	v_max_f32_e32 v216, v216, v95
	v_max_f32_e32 v161, v161, v216
	v_cmp_ge_f32_e32 vcc, s66, v161
	s_cmp_eq_u64 vcc, exec
	s_cbranch_scc0 .Lg1_rare1
	v_mov_b32_e32 v235, 1.0
